# y1 + DA loops stage the next K/V tile into LDS before the PV section instead of after it
# baseline (speedup 1.0000x reference)
; #define LAS __attribute__((address_space(3)))
; __device__ __forceinline__ unsigned cvt_pk_bf16(float lo, float hi) { f32x2_t v = {lo, hi}; bf16x2_t b = __builtin_convertvector(v, bf16x2_t); return __builtin_bit_cast(unsigned, b); }
; __device__ __forceinline__ float fast_exp2(float x) { return __builtin_amdgcn_exp2f(x); }
; template <int MODE> ...
;     ...
;             const float alpha = fast_exp2(mrun - mnew);
;             mrun = mnew;
;             float ps = 0.f;
; #pragma unroll
;             for (int r = 0; r < 16; ++r) { s0[r] = fast_exp2(s0[r] - mnew); s1[r] = fast_exp2(s1[r] - mnew); ps += s0[r] + s1[r]; }
;             lsum = lsum * alpha + ps;
; #pragma unroll
;             for (int i = 0; i < NDV; ++i)
; #pragma unroll
;                 for (int r = 0; r < 16; ++r) acc[i][r] *= alpha;
;             bf16x8 pf[2][2];
; #pragma unroll
;             for (int t = 0; t < 2; ++t) {
;                 u32x4 w0, w1;
;                 w0.x = cvt_pk_bf16(s0[8 * t + 0], s0[8 * t + 1]); w0.y = cvt_pk_bf16(s0[8 * t + 2], s0[8 * t + 3]); w0.z = cvt_pk_bf16(s0[8 * t + 4], s0[8 * t + 5]); w0.w = cvt_pk_bf16(s0[8 * t + 6], s0[8 * t + 7]);
;                 w1.x = cvt_pk_bf16(s1[8 * t + 0], s1[8 * t + 1]); w1.y = cvt_pk_bf16(s1[8 * t + 2], s1[8 * t + 3]); w1.z = cvt_pk_bf16(s1[8 * t + 4], s1[8 * t + 5]); w1.w = cvt_pk_bf16(s1[8 * t + 6], s1[8 * t + 7]);
;                 pf[0][t] = __builtin_bit_cast(bf16x8, w0); pf[1][t] = __builtin_bit_cast(bf16x8, w1);
;             }
;     ...
;             {
;                 bf16x8 vcur[4], vnxt[4];
;                 AT_LOADV(vcur, 0);
;     ...
;         if (more) {
;             LAS unsigned char* kb = lds + (bufsel ^ 1) * AT_BUF; LAS unsigned char* vb = kb + AT_KBYTES;
;             *(LAS u32x4*)(kb + kp_row0 * AT_KROW + kp_c * 16) = kr0; *(LAS u32x4*)(kb + (kp_row0 + 32) * AT_KROW + kp_c * 16) = kr1;
;             { LAS unsigned char* p0 = vb + vp_row0 * AT_VROW + vp_c * 16; LAS unsigned char* p1 = vb + (vp_row0 + 64) * AT_VROW + vp_c * 16;
;           *(LAS u32x2*)p0 = (u32x2){vr0.x, vr0.y}; *(LAS u32x2*)(p0 + 8) = (u32x2){vr0.z, vr0.w}; *(LAS u32x2*)p1 = (u32x2){vr1.x, vr1.y}; *(LAS u32x2*)(p1 + 8) = (u32x2){vr1.z, vr1.w}; }
.Lresc_keep_A:
	v_sub_f32_e32 v85, v152, v83
	v_exp_f32_e32 v152, v85
	v_sub_f32_e32 v85, v174, v83
	v_exp_f32_e32 v156, v85
	v_sub_f32_e32 v85, v153, v83
	v_exp_f32_e32 v88, v85
	v_sub_f32_e32 v85, v175, v83
	v_exp_f32_e32 v86, v85
	v_sub_f32_e32 v85, v150, v83
	v_exp_f32_e32 v150, v85
	v_sub_f32_e32 v85, v172, v83
	v_exp_f32_e32 v153, v85
	v_sub_f32_e32 v85, v151, v83
	v_exp_f32_e32 v92, v85
	v_sub_f32_e32 v85, v173, v83
	v_exp_f32_e32 v90, v85
	v_sub_f32_e32 v85, v170, v83
	v_exp_f32_e32 v151, v85
	v_sub_f32_e32 v85, v182, v83
	v_exp_f32_e32 v157, v85
	v_sub_f32_e32 v85, v171, v83
	v_exp_f32_e32 v96, v85
	v_sub_f32_e32 v85, v183, v83
	v_exp_f32_e32 v94, v85
	v_sub_f32_e32 v85, v176, v83
	v_exp_f32_e32 v158, v85
	v_sub_f32_e32 v85, v184, v83
	v_exp_f32_e32 v159, v85
	v_sub_f32_e32 v85, v177, v83
	v_sub_f32_e32 v0, v14, v83
	v_exp_f32_e32 v100, v85
	v_sub_f32_e32 v85, v185, v83
	v_exp_f32_e32 v110, v0
	v_sub_f32_e32 v0, v166, v83
	v_sub_f32_e32 v14, v167, v83
	v_exp_f32_e32 v98, v85
	v_sub_f32_e32 v85, v180, v83
	v_exp_f32_e32 v154, v0
	v_sub_f32_e32 v0, v15, v83
	v_exp_f32_e32 v80, v14
	v_sub_f32_e32 v14, v148, v83
	v_exp_f32_e32 v160, v85
	v_sub_f32_e32 v85, v188, v83
	v_exp_f32_e32 v0, v0
	v_exp_f32_e32 v111, v14
	v_sub_f32_e32 v14, v168, v83
	v_exp_f32_e32 v161, v85
	v_sub_f32_e32 v85, v181, v83
	v_exp_f32_e32 v155, v14
	v_sub_f32_e32 v14, v149, v83
	v_exp_f32_e32 v104, v85
	v_sub_f32_e32 v85, v189, v83
	v_exp_f32_e32 v84, v14
	v_sub_f32_e32 v14, v169, v83
	v_exp_f32_e32 v102, v85
	v_sub_f32_e32 v85, v178, v83
	v_add_f32_e32 v81, v154, v110
	v_exp_f32_e32 v14, v14
	v_exp_f32_e32 v162, v85
	v_sub_f32_e32 v85, v186, v83
	v_exp_f32_e32 v163, v85
	v_sub_f32_e32 v85, v179, v83
	v_pk_add_f32 v[108:109], v[80:81], v[0:1]
	v_exp_f32_e32 v148, v85
	v_sub_f32_e32 v85, v187, v83
	v_pk_add_f32 v[108:109], v[108:109], v[108:109] op_sel_hi:[0,1]
	v_add_f32_e32 v15, v155, v111
	v_exp_f32_e32 v106, v85
	v_mov_b32_e32 v85, v109
	v_pk_add_f32 v[108:109], v[14:15], v[84:85]
	v_add_f32_e32 v87, v156, v152
	v_pk_add_f32 v[108:109], v[108:109], v[108:109] op_sel_hi:[0,1]
	v_mov_b32_e32 v89, v109
	v_pk_add_f32 v[108:109], v[86:87], v[88:89]
	v_add_f32_e32 v91, v153, v150
	v_pk_add_f32 v[108:109], v[108:109], v[108:109] op_sel_hi:[0,1]
	v_mov_b32_e32 v93, v109
	v_pk_add_f32 v[108:109], v[90:91], v[92:93]
	v_add_f32_e32 v95, v157, v151
	v_pk_add_f32 v[108:109], v[108:109], v[108:109] op_sel_hi:[0,1]
	v_mov_b32_e32 v97, v109
	v_pk_add_f32 v[108:109], v[94:95], v[96:97]
	v_add_f32_e32 v99, v159, v158
	v_pk_add_f32 v[108:109], v[108:109], v[108:109] op_sel_hi:[0,1]
	v_mov_b32_e32 v101, v109
	v_pk_add_f32 v[108:109], v[98:99], v[100:101]
	v_add_f32_e32 v103, v161, v160
	v_pk_add_f32 v[108:109], v[108:109], v[108:109] op_sel_hi:[0,1]
	v_mov_b32_e32 v105, v109
	v_pk_add_f32 v[108:109], v[102:103], v[104:105]
	v_add_f32_e32 v107, v163, v162
	v_pk_add_f32 v[108:109], v[108:109], v[108:109] op_sel_hi:[0,1]
	v_mov_b32_e32 v149, v109
	v_pk_add_f32 v[108:109], v[106:107], v[148:149]
	v_cvt_pk_bf16_f32 v87, v153, v90
	v_add_f32_e32 v15, v108, v109
	v_cvt_pk_bf16_f32 v108, v110, v0
	v_add3_u32 v0, s30, v141, v192
	v_add_u32_e32 v0, 0x4000, v0
	v_cvt_pk_bf16_f32 v109, v111, v84
	v_cvt_pk_bf16_f32 v110, v152, v88
	v_cvt_pk_bf16_f32 v111, v150, v92
	v_cvt_pk_bf16_f32 v88, v151, v96
	v_cvt_pk_bf16_f32 v89, v158, v100
	v_cvt_pk_bf16_f32 v90, v160, v104
	v_cvt_pk_bf16_f32 v91, v162, v148
	v_cvt_pk_bf16_f32 v92, v157, v94
	v_cvt_pk_bf16_f32 v93, v159, v98
	v_cvt_pk_bf16_f32 v94, v161, v102
	v_cvt_pk_bf16_f32 v95, v163, v106
	s_xor_b32 vcc_lo, s29, 1
	s_mul_i32 vcc_lo, vcc_lo, 0x8800
	v_add3_u32 v218, vcc_lo, v137, v138
	v_add3_u32 v219, vcc_lo, v195, v138
	v_add3_u32 v220, vcc_lo, v196, v140
	v_add_u32_e32 v221, 0x4400, v220
	v_add_u32_e32 v220, 0x6600, v220
	s_waitcnt vmcnt(3)
	ds_write_b128 v218, v[2:5]
	s_waitcnt vmcnt(2)
	ds_write_b128 v219, v[6:9]
	s_waitcnt vmcnt(1)
	ds_write2_b64 v221, v[10:11], v[12:13] offset1:1
	s_waitcnt vmcnt(0)
	ds_write2_b64 v220, v[128:129], v[130:131] offset1:1
	ds_read2_b64 v[96:99], v0 offset0:128 offset1:130
	ds_read2_b64 v[100:103], v0 offset0:132 offset1:134
	ds_read2_b64 v[104:107], v0 offset0:136 offset1:138
	ds_read2_b64 v[148:151], v0 offset0:140 offset1:142
	v_add3_u32 v0, s30, v192, v141
	v_cvt_pk_bf16_f32 v85, v155, v14
	v_add_u32_e32 v14, 0x5000, v0
	v_cvt_pk_bf16_f32 v84, v154, v80
	v_cvt_pk_bf16_f32 v86, v156, v86
	ds_read2_b64 v[152:155], v14 offset0:160 offset1:162
	ds_read2_b64 v[156:159], v14 offset0:164 offset1:166
	ds_read2_b64 v[160:163], v14 offset0:168 offset1:170
	ds_read2_b64 v[164:167], v14 offset0:172 offset1:174
	v_sub_f32_e32 v82, v198, v83
	v_exp_f32_e32 v82, v82
	s_nop 0
	s_cmp_eq_u64 s[100:101], 0
	s_cbranch_scc1 .Lresc_skip_A
	v_pk_mul_f32 v[78:79], v[78:79], v[82:83] op_sel_hi:[1,0]
	v_pk_mul_f32 v[76:77], v[76:77], v[82:83] op_sel_hi:[1,0]
	v_pk_mul_f32 v[74:75], v[74:75], v[82:83] op_sel_hi:[1,0]
	v_pk_mul_f32 v[72:73], v[72:73], v[82:83] op_sel_hi:[1,0]
	v_pk_mul_f32 v[70:71], v[70:71], v[82:83] op_sel_hi:[1,0]
	v_pk_mul_f32 v[68:69], v[68:69], v[82:83] op_sel_hi:[1,0]
	v_pk_mul_f32 v[66:67], v[66:67], v[82:83] op_sel_hi:[1,0]
	v_pk_mul_f32 v[64:65], v[64:65], v[82:83] op_sel_hi:[1,0]
	v_pk_mul_f32 v[62:63], v[62:63], v[82:83] op_sel_hi:[1,0]
	v_pk_mul_f32 v[60:61], v[60:61], v[82:83] op_sel_hi:[1,0]
	v_pk_mul_f32 v[58:59], v[58:59], v[82:83] op_sel_hi:[1,0]
	v_pk_mul_f32 v[56:57], v[56:57], v[82:83] op_sel_hi:[1,0]
	v_pk_mul_f32 v[54:55], v[54:55], v[82:83] op_sel_hi:[1,0]
	v_pk_mul_f32 v[52:53], v[52:53], v[82:83] op_sel_hi:[1,0]
	v_pk_mul_f32 v[50:51], v[50:51], v[82:83] op_sel_hi:[1,0]
	v_pk_mul_f32 v[48:49], v[48:49], v[82:83] op_sel_hi:[1,0]
	v_pk_mul_f32 v[46:47], v[46:47], v[82:83] op_sel_hi:[1,0]
	v_pk_mul_f32 v[44:45], v[44:45], v[82:83] op_sel_hi:[1,0]
	v_pk_mul_f32 v[42:43], v[42:43], v[82:83] op_sel_hi:[1,0]
	v_pk_mul_f32 v[40:41], v[40:41], v[82:83] op_sel_hi:[1,0]
	v_pk_mul_f32 v[38:39], v[38:39], v[82:83] op_sel_hi:[1,0]
	v_pk_mul_f32 v[36:37], v[36:37], v[82:83] op_sel_hi:[1,0]
	v_pk_mul_f32 v[34:35], v[34:35], v[82:83] op_sel_hi:[1,0]
	v_pk_mul_f32 v[32:33], v[32:33], v[82:83] op_sel_hi:[1,0]
	v_pk_mul_f32 v[30:31], v[30:31], v[82:83] op_sel_hi:[1,0]
	v_pk_mul_f32 v[28:29], v[28:29], v[82:83] op_sel_hi:[1,0]
	v_pk_mul_f32 v[26:27], v[26:27], v[82:83] op_sel_hi:[1,0]
	v_pk_mul_f32 v[24:25], v[24:25], v[82:83] op_sel_hi:[1,0]
	v_pk_mul_f32 v[22:23], v[22:23], v[82:83] op_sel_hi:[1,0]
	v_pk_mul_f32 v[20:21], v[20:21], v[82:83] op_sel_hi:[1,0]
	v_pk_mul_f32 v[18:19], v[18:19], v[82:83] op_sel_hi:[1,0]
	v_pk_mul_f32 v[16:17], v[16:17], v[82:83] op_sel_hi:[1,0]
; template <int MODE> ...
;     ...
;     for (int kt = kt_lo; kt <= kt_hi; ++kt) {
;     ...
;             {
;                 bf16x8 vcur[4], vnxt[4];
;                 AT_LOADV(vcur, 0);
; #pragma unroll
;                 for (int dvb = 0; dvb < NDV; ++dvb) {
;                     if (dvb + 1 < NDV) AT_LOADV(vnxt, dvb + 1);
;                     __builtin_amdgcn_sched_barrier(0);
; #pragma unroll
;                     for (int i = 0; i < 4; ++i) acc[dvb] = __builtin_amdgcn_mfma_f32_32x32x16_bf16(vcur[i], pf[i >> 1][i & 1], acc[dvb], 0, 0, 0);
;                     __builtin_amdgcn_sched_barrier(0);
; #pragma unroll
;                     for (int i = 0; i < 4; ++i) vcur[i] = vnxt[i];
;                 }
;             }
.Lresc_skip_A:
	s_waitcnt lgkmcnt(7)
	v_mfma_f32_32x32x16_bf16 v[64:79], v[96:99], v[108:111], v[64:79]
	s_waitcnt lgkmcnt(6)
	v_mfma_f32_32x32x16_bf16 v[64:79], v[100:103], v[88:91], v[64:79]
	s_waitcnt lgkmcnt(5)
	v_mfma_f32_32x32x16_bf16 v[64:79], v[104:107], v[84:87], v[64:79]
	s_waitcnt lgkmcnt(4)
	v_mfma_f32_32x32x16_bf16 v[64:79], v[148:151], v[92:95], v[64:79]
	v_add_u32_e32 v14, 0x6000, v0
	ds_read2_b64 v[96:99], v14 offset0:192 offset1:194
	ds_read2_b64 v[100:103], v14 offset0:196 offset1:198
	ds_read2_b64 v[104:107], v14 offset0:200 offset1:202
	ds_read2_b64 v[148:151], v14 offset0:204 offset1:206
	s_waitcnt lgkmcnt(7)
	v_mfma_f32_32x32x16_bf16 v[48:63], v[152:155], v[108:111], v[48:63]
	s_waitcnt lgkmcnt(6)
	v_mfma_f32_32x32x16_bf16 v[48:63], v[156:159], v[88:91], v[48:63]
	s_waitcnt lgkmcnt(5)
	v_mfma_f32_32x32x16_bf16 v[48:63], v[160:163], v[84:87], v[48:63]
	s_waitcnt lgkmcnt(4)
	v_mfma_f32_32x32x16_bf16 v[48:63], v[164:167], v[92:95], v[48:63]
	v_add_u32_e32 v0, 0x7000, v0
	ds_read2_b64 v[152:155], v0 offset0:224 offset1:226
	ds_read2_b64 v[156:159], v0 offset0:228 offset1:230
	ds_read2_b64 v[160:163], v0 offset0:232 offset1:234
	ds_read2_b64 v[164:167], v0 offset0:236 offset1:238
	s_waitcnt lgkmcnt(7)
	v_mfma_f32_32x32x16_bf16 v[32:47], v[96:99], v[108:111], v[32:47]
	s_waitcnt lgkmcnt(6)
	v_mfma_f32_32x32x16_bf16 v[32:47], v[100:103], v[88:91], v[32:47]
	s_waitcnt lgkmcnt(5)
	v_mfma_f32_32x32x16_bf16 v[32:47], v[104:107], v[84:87], v[32:47]
	s_waitcnt lgkmcnt(4)
	v_mfma_f32_32x32x16_bf16 v[32:47], v[148:151], v[92:95], v[32:47]
	s_waitcnt lgkmcnt(3)
	v_mfma_f32_32x32x16_bf16 v[16:31], v[152:155], v[108:111], v[16:31]
	s_waitcnt lgkmcnt(2)
	v_mfma_f32_32x32x16_bf16 v[16:31], v[156:159], v[88:91], v[16:31]
	s_waitcnt lgkmcnt(1)
	v_mfma_f32_32x32x16_bf16 v[16:31], v[160:163], v[84:87], v[16:31]
	s_waitcnt lgkmcnt(0)
	v_mfma_f32_32x32x16_bf16 v[16:31], v[164:167], v[92:95], v[16:31]
	v_fmac_f32_e32 v15, v139, v82
	v_mov_b32_e32 v198, v83
	v_mov_b32_e32 v139, v15
	s_add_i32 s25, s25, 1
	v_lshl_add_u64 v[142:143], v[142:143], 0, s[96:97]
	v_subrev_u32_e32 v199, 64, v199
	v_add_u32_e32 v200, 0xffffff00, v200
	v_lshl_add_u64 v[144:145], v[144:145], 0, s[94:95]
	s_cmp_eq_u32 s33, s28
	s_cbranch_scc1 .LBB0_389
	s_mov_b32 s14, s28
	s_branch .LBB0_381

; #define LAS __attribute__((address_space(3)))
; __device__ __forceinline__ unsigned cvt_pk_bf16(float lo, float hi) { f32x2_t v = {lo, hi}; bf16x2_t b = __builtin_convertvector(v, bf16x2_t); return __builtin_bit_cast(unsigned, b); }
; __device__ __forceinline__ float fast_exp2(float x) { return __builtin_amdgcn_exp2f(x); }
; template <int MODE> ...
;     ...
;             const float alpha = fast_exp2(mrun - mnew);
;             mrun = mnew;
;             float ps = 0.f;
; #pragma unroll
;             for (int r = 0; r < 16; ++r) { s0[r] = fast_exp2(s0[r] - mnew); s1[r] = fast_exp2(s1[r] - mnew); ps += s0[r] + s1[r]; }
;             lsum = lsum * alpha + ps;
; #pragma unroll
;             for (int i = 0; i < NDV; ++i)
; #pragma unroll
;                 for (int r = 0; r < 16; ++r) acc[i][r] *= alpha;
;             bf16x8 pf[2][2];
; #pragma unroll
;             for (int t = 0; t < 2; ++t) {
;                 u32x4 w0, w1;
;                 w0.x = cvt_pk_bf16(s0[8 * t + 0], s0[8 * t + 1]); w0.y = cvt_pk_bf16(s0[8 * t + 2], s0[8 * t + 3]); w0.z = cvt_pk_bf16(s0[8 * t + 4], s0[8 * t + 5]); w0.w = cvt_pk_bf16(s0[8 * t + 6], s0[8 * t + 7]);
;                 w1.x = cvt_pk_bf16(s1[8 * t + 0], s1[8 * t + 1]); w1.y = cvt_pk_bf16(s1[8 * t + 2], s1[8 * t + 3]); w1.z = cvt_pk_bf16(s1[8 * t + 4], s1[8 * t + 5]); w1.w = cvt_pk_bf16(s1[8 * t + 6], s1[8 * t + 7]);
;                 pf[0][t] = __builtin_bit_cast(bf16x8, w0); pf[1][t] = __builtin_bit_cast(bf16x8, w1);
;             }
;     ...
;             {
;                 bf16x8 vcur[4], vnxt[4];
;                 AT_LOADV(vcur, 0);
;     ...
;         if (more) {
;             LAS unsigned char* kb = lds + (bufsel ^ 1) * AT_BUF; LAS unsigned char* vb = kb + AT_KBYTES;
;             *(LAS u32x4*)(kb + kp_row0 * AT_KROW + kp_c * 16) = kr0; *(LAS u32x4*)(kb + (kp_row0 + 32) * AT_KROW + kp_c * 16) = kr1;
;             { LAS unsigned char* p0 = vb + vp_row0 * AT_VROW + vp_c * 16; LAS unsigned char* p1 = vb + (vp_row0 + 64) * AT_VROW + vp_c * 16;
;           *(LAS u32x2*)p0 = (u32x2){vr0.x, vr0.y}; *(LAS u32x2*)(p0 + 8) = (u32x2){vr0.z, vr0.w}; *(LAS u32x2*)p1 = (u32x2){vr1.x, vr1.y}; *(LAS u32x2*)(p1 + 8) = (u32x2){vr1.z, vr1.w}; }
.Lresc_keep_B:
	v_sub_f32_e32 v85, v152, v83
	v_exp_f32_e32 v152, v85
	v_sub_f32_e32 v85, v174, v83
	v_exp_f32_e32 v155, v85
	v_sub_f32_e32 v85, v153, v83
	v_exp_f32_e32 v88, v85
	v_sub_f32_e32 v85, v175, v83
	v_exp_f32_e32 v86, v85
	v_sub_f32_e32 v85, v150, v83
	v_exp_f32_e32 v150, v85
	v_sub_f32_e32 v85, v172, v83
	v_exp_f32_e32 v153, v85
	v_sub_f32_e32 v85, v151, v83
	v_exp_f32_e32 v92, v85
	v_sub_f32_e32 v85, v173, v83
	v_exp_f32_e32 v90, v85
	v_sub_f32_e32 v85, v170, v83
	v_exp_f32_e32 v151, v85
	v_sub_f32_e32 v85, v182, v83
	v_exp_f32_e32 v156, v85
	v_sub_f32_e32 v85, v171, v83
	v_exp_f32_e32 v96, v85
	v_sub_f32_e32 v85, v183, v83
	v_exp_f32_e32 v94, v85
	v_sub_f32_e32 v85, v176, v83
	v_exp_f32_e32 v157, v85
	v_sub_f32_e32 v85, v184, v83
	v_exp_f32_e32 v158, v85
	v_sub_f32_e32 v85, v177, v83
	v_sub_f32_e32 v0, v14, v83
	v_exp_f32_e32 v100, v85
	v_sub_f32_e32 v85, v185, v83
	v_exp_f32_e32 v110, v0
	v_sub_f32_e32 v0, v166, v83
	v_sub_f32_e32 v14, v167, v83
	v_exp_f32_e32 v98, v85
	v_sub_f32_e32 v85, v180, v83
	v_exp_f32_e32 v137, v0
	v_sub_f32_e32 v0, v15, v83
	v_exp_f32_e32 v80, v14
	v_sub_f32_e32 v14, v148, v83
	v_exp_f32_e32 v159, v85
	v_sub_f32_e32 v85, v188, v83
	v_exp_f32_e32 v0, v0
	v_exp_f32_e32 v111, v14
	v_sub_f32_e32 v14, v168, v83
	v_exp_f32_e32 v160, v85
	v_sub_f32_e32 v85, v181, v83
	v_exp_f32_e32 v154, v14
	v_sub_f32_e32 v14, v149, v83
	v_exp_f32_e32 v104, v85
	v_sub_f32_e32 v85, v189, v83
	v_exp_f32_e32 v84, v14
	v_sub_f32_e32 v14, v169, v83
	v_exp_f32_e32 v102, v85
	v_sub_f32_e32 v85, v178, v83
	v_add_f32_e32 v81, v137, v110
	v_exp_f32_e32 v14, v14
	v_exp_f32_e32 v161, v85
	v_sub_f32_e32 v85, v186, v83
	v_exp_f32_e32 v162, v85
	v_sub_f32_e32 v85, v179, v83
	v_pk_add_f32 v[108:109], v[80:81], v[0:1]
	v_exp_f32_e32 v148, v85
	v_sub_f32_e32 v85, v187, v83
	v_pk_add_f32 v[108:109], v[108:109], v[108:109] op_sel_hi:[0,1]
	v_add_f32_e32 v15, v154, v111
	v_exp_f32_e32 v106, v85
	v_mov_b32_e32 v85, v109
	v_pk_add_f32 v[108:109], v[14:15], v[84:85]
	v_add_f32_e32 v87, v155, v152
	v_pk_add_f32 v[108:109], v[108:109], v[108:109] op_sel_hi:[0,1]
	v_mov_b32_e32 v89, v109
	v_pk_add_f32 v[108:109], v[86:87], v[88:89]
	v_add_f32_e32 v91, v153, v150
	v_pk_add_f32 v[108:109], v[108:109], v[108:109] op_sel_hi:[0,1]
	v_mov_b32_e32 v93, v109
	v_pk_add_f32 v[108:109], v[90:91], v[92:93]
	v_add_f32_e32 v95, v156, v151
	v_pk_add_f32 v[108:109], v[108:109], v[108:109] op_sel_hi:[0,1]
	v_mov_b32_e32 v97, v109
	v_pk_add_f32 v[108:109], v[94:95], v[96:97]
	v_add_f32_e32 v99, v158, v157
	v_pk_add_f32 v[108:109], v[108:109], v[108:109] op_sel_hi:[0,1]
	v_mov_b32_e32 v101, v109
	v_pk_add_f32 v[108:109], v[98:99], v[100:101]
	v_add_f32_e32 v103, v160, v159
	v_pk_add_f32 v[108:109], v[108:109], v[108:109] op_sel_hi:[0,1]
	v_mov_b32_e32 v105, v109
	v_pk_add_f32 v[108:109], v[102:103], v[104:105]
	v_add_f32_e32 v107, v162, v161
	v_pk_add_f32 v[108:109], v[108:109], v[108:109] op_sel_hi:[0,1]
	v_mov_b32_e32 v149, v109
	v_pk_add_f32 v[108:109], v[106:107], v[148:149]
	v_cvt_pk_bf16_f32 v87, v153, v90
	v_add_f32_e32 v15, v108, v109
	v_cvt_pk_bf16_f32 v108, v110, v0
	v_add3_u32 v0, s12, v194, v141
	v_add_u32_e32 v0, 0x4000, v0
	v_cvt_pk_bf16_f32 v109, v111, v84
	v_cvt_pk_bf16_f32 v110, v152, v88
	v_cvt_pk_bf16_f32 v111, v150, v92
	v_cvt_pk_bf16_f32 v88, v151, v96
	v_cvt_pk_bf16_f32 v89, v157, v100
	v_cvt_pk_bf16_f32 v90, v159, v104
	v_cvt_pk_bf16_f32 v91, v161, v148
	v_cvt_pk_bf16_f32 v92, v156, v94
	v_cvt_pk_bf16_f32 v93, v158, v98
	v_cvt_pk_bf16_f32 v94, v160, v102
	v_cvt_pk_bf16_f32 v95, v162, v106
	s_xor_b32 vcc_lo, s9, 1
	s_mul_i32 vcc_lo, vcc_lo, 0x8800
	v_add3_u32 v218, vcc_lo, v198, v136
	v_add3_u32 v219, vcc_lo, v200, v136
	v_add3_u32 v220, vcc_lo, v199, v138
	v_add_u32_e32 v221, 0x4400, v220
	v_add_u32_e32 v220, 0x6600, v220
	s_waitcnt vmcnt(3)
	ds_write_b128 v218, v[2:5]
	s_waitcnt vmcnt(2)
	ds_write_b128 v219, v[6:9]
	s_waitcnt vmcnt(1)
	ds_write2_b64 v221, v[10:11], v[12:13] offset1:1
	s_waitcnt vmcnt(0)
	ds_write2_b64 v220, v[128:129], v[130:131] offset1:1
	ds_read2_b64 v[96:99], v0 offset0:128 offset1:130
	ds_read2_b64 v[100:103], v0 offset0:132 offset1:134
	ds_read2_b64 v[104:107], v0 offset0:136 offset1:138
	ds_read2_b64 v[148:151], v0 offset0:140 offset1:142
	v_add3_u32 v0, s12, v141, v194
	v_cvt_pk_bf16_f32 v85, v154, v14
	v_add_u32_e32 v14, 0x5000, v0
	v_cvt_pk_bf16_f32 v86, v155, v86
	ds_read2_b64 v[152:155], v14 offset0:160 offset1:162
	ds_read2_b64 v[156:159], v14 offset0:164 offset1:166
	ds_read2_b64 v[160:163], v14 offset0:168 offset1:170
	ds_read2_b64 v[164:167], v14 offset0:172 offset1:174
	v_sub_f32_e32 v82, v196, v83
	v_exp_f32_e32 v82, v82
	v_cvt_pk_bf16_f32 v84, v137, v80
	s_cmp_eq_u64 s[100:101], 0
	s_cbranch_scc1 .Lresc_skip_B
	v_pk_mul_f32 v[78:79], v[78:79], v[82:83] op_sel_hi:[1,0]
	v_pk_mul_f32 v[76:77], v[76:77], v[82:83] op_sel_hi:[1,0]
	v_pk_mul_f32 v[74:75], v[74:75], v[82:83] op_sel_hi:[1,0]
	v_pk_mul_f32 v[72:73], v[72:73], v[82:83] op_sel_hi:[1,0]
	v_pk_mul_f32 v[70:71], v[70:71], v[82:83] op_sel_hi:[1,0]
	v_pk_mul_f32 v[68:69], v[68:69], v[82:83] op_sel_hi:[1,0]
	v_pk_mul_f32 v[66:67], v[66:67], v[82:83] op_sel_hi:[1,0]
	v_pk_mul_f32 v[64:65], v[64:65], v[82:83] op_sel_hi:[1,0]
	v_pk_mul_f32 v[62:63], v[62:63], v[82:83] op_sel_hi:[1,0]
	v_pk_mul_f32 v[60:61], v[60:61], v[82:83] op_sel_hi:[1,0]
	v_pk_mul_f32 v[58:59], v[58:59], v[82:83] op_sel_hi:[1,0]
	v_pk_mul_f32 v[56:57], v[56:57], v[82:83] op_sel_hi:[1,0]
	v_pk_mul_f32 v[54:55], v[54:55], v[82:83] op_sel_hi:[1,0]
	v_pk_mul_f32 v[52:53], v[52:53], v[82:83] op_sel_hi:[1,0]
	v_pk_mul_f32 v[50:51], v[50:51], v[82:83] op_sel_hi:[1,0]
	v_pk_mul_f32 v[48:49], v[48:49], v[82:83] op_sel_hi:[1,0]
	v_pk_mul_f32 v[46:47], v[46:47], v[82:83] op_sel_hi:[1,0]
	v_pk_mul_f32 v[44:45], v[44:45], v[82:83] op_sel_hi:[1,0]
	v_pk_mul_f32 v[42:43], v[42:43], v[82:83] op_sel_hi:[1,0]
	v_pk_mul_f32 v[40:41], v[40:41], v[82:83] op_sel_hi:[1,0]
	v_pk_mul_f32 v[38:39], v[38:39], v[82:83] op_sel_hi:[1,0]
	v_pk_mul_f32 v[36:37], v[36:37], v[82:83] op_sel_hi:[1,0]
	v_pk_mul_f32 v[34:35], v[34:35], v[82:83] op_sel_hi:[1,0]
	v_pk_mul_f32 v[32:33], v[32:33], v[82:83] op_sel_hi:[1,0]
	v_pk_mul_f32 v[30:31], v[30:31], v[82:83] op_sel_hi:[1,0]
	v_pk_mul_f32 v[28:29], v[28:29], v[82:83] op_sel_hi:[1,0]
	v_pk_mul_f32 v[26:27], v[26:27], v[82:83] op_sel_hi:[1,0]
	v_pk_mul_f32 v[24:25], v[24:25], v[82:83] op_sel_hi:[1,0]
	v_pk_mul_f32 v[22:23], v[22:23], v[82:83] op_sel_hi:[1,0]
	v_pk_mul_f32 v[20:21], v[20:21], v[82:83] op_sel_hi:[1,0]
	v_pk_mul_f32 v[18:19], v[18:19], v[82:83] op_sel_hi:[1,0]
	v_pk_mul_f32 v[16:17], v[16:17], v[82:83] op_sel_hi:[1,0]
; template <int MODE> ...
;     ...
;     for (int kt = kt_lo; kt <= kt_hi; ++kt) {
;     ...
;             {
;                 bf16x8 vcur[4], vnxt[4];
;                 AT_LOADV(vcur, 0);
; #pragma unroll
;                 for (int dvb = 0; dvb < NDV; ++dvb) {
;                     if (dvb + 1 < NDV) AT_LOADV(vnxt, dvb + 1);
;                     __builtin_amdgcn_sched_barrier(0);
; #pragma unroll
;                     for (int i = 0; i < 4; ++i) acc[dvb] = __builtin_amdgcn_mfma_f32_32x32x16_bf16(vcur[i], pf[i >> 1][i & 1], acc[dvb], 0, 0, 0);
;                     __builtin_amdgcn_sched_barrier(0);
; #pragma unroll
;                     for (int i = 0; i < 4; ++i) vcur[i] = vnxt[i];
;                 }
;             }
.Lresc_skip_B:
	s_waitcnt lgkmcnt(7)
	v_mfma_f32_32x32x16_bf16 v[64:79], v[96:99], v[108:111], v[64:79]
	s_waitcnt lgkmcnt(6)
	v_mfma_f32_32x32x16_bf16 v[64:79], v[100:103], v[88:91], v[64:79]
	s_waitcnt lgkmcnt(5)
	v_mfma_f32_32x32x16_bf16 v[64:79], v[104:107], v[84:87], v[64:79]
	s_waitcnt lgkmcnt(4)
	v_mfma_f32_32x32x16_bf16 v[64:79], v[148:151], v[92:95], v[64:79]
	v_add_u32_e32 v14, 0x6000, v0
	ds_read2_b64 v[96:99], v14 offset0:192 offset1:194
	ds_read2_b64 v[100:103], v14 offset0:196 offset1:198
	ds_read2_b64 v[104:107], v14 offset0:200 offset1:202
	ds_read2_b64 v[148:151], v14 offset0:204 offset1:206
	s_waitcnt lgkmcnt(7)
	v_mfma_f32_32x32x16_bf16 v[48:63], v[152:155], v[108:111], v[48:63]
	s_waitcnt lgkmcnt(6)
	v_mfma_f32_32x32x16_bf16 v[48:63], v[156:159], v[88:91], v[48:63]
	s_waitcnt lgkmcnt(5)
	v_mfma_f32_32x32x16_bf16 v[48:63], v[160:163], v[84:87], v[48:63]
	s_waitcnt lgkmcnt(4)
	v_mfma_f32_32x32x16_bf16 v[48:63], v[164:167], v[92:95], v[48:63]
	v_add_u32_e32 v0, 0x7000, v0
	ds_read2_b64 v[152:155], v0 offset0:224 offset1:226
	ds_read2_b64 v[156:159], v0 offset0:228 offset1:230
	ds_read2_b64 v[160:163], v0 offset0:232 offset1:234
	ds_read2_b64 v[164:167], v0 offset0:236 offset1:238
	s_waitcnt lgkmcnt(7)
	v_mfma_f32_32x32x16_bf16 v[32:47], v[96:99], v[108:111], v[32:47]
	s_waitcnt lgkmcnt(6)
	v_mfma_f32_32x32x16_bf16 v[32:47], v[100:103], v[88:91], v[32:47]
	s_waitcnt lgkmcnt(5)
	v_mfma_f32_32x32x16_bf16 v[32:47], v[104:107], v[84:87], v[32:47]
	s_waitcnt lgkmcnt(4)
	v_mfma_f32_32x32x16_bf16 v[32:47], v[148:151], v[92:95], v[32:47]
	s_waitcnt lgkmcnt(3)
	v_mfma_f32_32x32x16_bf16 v[16:31], v[152:155], v[108:111], v[16:31]
	s_waitcnt lgkmcnt(2)
	v_mfma_f32_32x32x16_bf16 v[16:31], v[156:159], v[88:91], v[16:31]
	s_waitcnt lgkmcnt(1)
	v_mfma_f32_32x32x16_bf16 v[16:31], v[160:163], v[84:87], v[16:31]
	s_waitcnt lgkmcnt(0)
	v_mfma_f32_32x32x16_bf16 v[16:31], v[164:167], v[92:95], v[16:31]
	v_fmac_f32_e32 v15, v139, v82
	v_mov_b32_e32 v196, v83
	v_mov_b32_e32 v139, v15
	s_add_i32 s19, s19, 1
	v_lshl_add_u64 v[142:143], v[142:143], 0, s[96:97]
	v_subrev_u32_e32 v201, 64, v201
	v_add_u32_e32 v202, 0xffffff00, v202
	v_lshl_add_u64 v[144:145], v[144:145], 0, s[94:95]
	s_cmp_eq_u32 s89, s8
	s_cbranch_scc1 .LBB0_410
	s_mov_b32 s0, s8
	s_branch .LBB0_402
